# tile order variant: 16 row panels x 2 column tiles per XCD round (each weight tile shared by 16 CUs)
# baseline (speedup 1.0000x reference)
.LBB0_66:
	s_or_b64 exec, exec, s[4:5]
	s_mov_b64 s[4:5], s[0:1]
	v_mov_b32_e32 v8, v157
	s_cmpk_lt_i32 s2, 0xb00
	s_cselect_b64 s[24:25], -1, 0
	s_cmpk_gt_i32 s2, 0xaff
	v_readfirstlane_b32 s20, v8
	s_cbranch_scc1 .LBB0_84
	v_lshlrev_b32_e32 v0, 4, v8
	v_add_u32_e32 v1, 0x2000, v0
	v_ashrrev_i32_e32 v2, 31, v1
	v_lshrrev_b32_e32 v2, 22, v2
	v_add_u32_e32 v2, v1, v2
	v_ashrrev_i32_e32 v9, 10, v2
	v_mul_i32_i24_e32 v2, 0x400, v9
	v_sub_u32_e32 v1, v1, v2
	v_lshrrev_b32_e32 v2, 4, v1
	v_bitop3_b32 v1, v2, v1, 32 bitop3:0x6c
	v_ashrrev_i32_e32 v2, 31, v1
	v_lshrrev_b32_e32 v2, 26, v2
	v_add_u32_e32 v2, v1, v2
	v_lshlrev_b32_e32 v3, 3, v9
	v_ashrrev_i32_e32 v10, 6, v2
	v_and_b32_e32 v3, -16, v3
	v_add_u32_e32 v3, v10, v3
	v_and_b32_e32 v4, 3, v10
	s_mov_b32 s8, 0x1fffe0
	v_lshrrev_b32_e32 v5, 2, v3
	v_lshlrev_b32_e32 v6, 1, v3
	v_and_b32_e32 v2, 0xc0, v2
	v_and_or_b32 v4, v3, s8, v4
	v_and_b32_e32 v5, 4, v5
	v_and_b32_e32 v6, 24, v6
	v_sub_u32_e32 v1, v1, v2
	v_mov_b32_e32 v2, 1
	v_or3_b32 v4, v4, v5, v6
	v_lshlrev_b32_e32 v5, 5, v9
	v_ashrrev_i16_sdwa v1, v2, sext(v1) dst_sel:DWORD dst_unused:UNUSED_PAD src0_sel:DWORD src1_sel:BYTE_0
	v_and_b32_e32 v5, 32, v5
	v_bfe_i32 v11, v1, 0, 16
	v_add_lshl_u32 v1, v5, v11, 1
	v_lshl_add_u32 v128, v4, 11, v1
	v_lshrrev_b32_e32 v250, 3, v157
	v_and_b32_e32 v251, 6, v250
	v_and_b32_e32 v252, 7, v157
	v_xor_b32_e32 v251, v251, v252
	v_lshlrev_b32_e32 v251, 4, v251
	v_and_b32_e32 v252, 12, v250
	v_lshlrev_b32_e32 v252, 1, v252
	v_and_b32_e32 v253, 16, v250
	v_lshrrev_b32_e32 v253, 2, v253
	v_or_b32_e32 v252, v252, v253
	v_and_b32_e32 v253, 35, v250
	v_or_b32_e32 v250, v252, v253
	v_mul_u32_u24_e32 v250, 0x800, v250
	v_add_u32_e32 v128, v250, v251
	v_add_u32_e32 v128, 0x20000, v128
	v_lshl_add_u32 v130, v3, 11, v1
	v_lshrrev_b32_e32 v250, 3, v157
	v_and_b32_e32 v251, 6, v250
	v_and_b32_e32 v252, 7, v157
	v_xor_b32_e32 v251, v251, v252
	v_lshlrev_b32_e32 v251, 4, v251
	v_mul_u32_u24_e32 v250, 0x800, v250
	v_add_u32_e32 v130, v250, v251
	v_add_u32_e32 v130, 0x20000, v130
	v_bfe_i32 v1, v8, 27, 1
	v_lshrrev_b32_e32 v1, 22, v1
	v_add_u32_e32 v1, v0, v1
	s_load_dwordx2 s[4:5], s[4:5], 0x80
	v_and_b32_e32 v1, 0xfffffc00, v1
	v_sub_u32_e32 v0, v0, v1
	v_lshrrev_b32_e32 v1, 4, v0
	v_ashrrev_i32_e32 v3, 31, v8
	v_bitop3_b32 v0, v1, v0, 32 bitop3:0x6c
	v_lshrrev_b32_e32 v3, 26, v3
	v_ashrrev_i32_e32 v1, 31, v0
	v_add_u32_e32 v3, v8, v3
	s_waitcnt lgkmcnt(0)
	s_add_u32 s3, s4, 0x6000000
	v_lshrrev_b32_e32 v1, 26, v1
	v_ashrrev_i32_e32 v13, 6, v3
	s_addc_u32 s35, s5, 0
	v_add_u32_e32 v1, v0, v1
	v_lshlrev_b32_e32 v3, 3, v13
	s_add_u32 s50, s4, 0x400000
	v_ashrrev_i32_e32 v12, 6, v1
	v_and_b32_e32 v3, -16, v3
	s_addc_u32 s51, s5, 0
	v_add_u32_e32 v3, v12, v3
	v_and_b32_e32 v4, 3, v12
	s_ashr_i32 s53, s2, 31
	v_and_or_b32 v4, v3, s8, v4
	s_lshr_b32 s8, s53, 29
	s_add_i32 s8, s2, s8
	s_ashr_i32 s17, s20, 6
	s_ashr_i32 s9, s8, 3
	s_and_b32 s8, s8, -8
	s_ashr_i32 s21, s20, 8
	s_lshl_b32 s52, s17, 10
	s_sub_i32 s8, s2, s8
	s_cmp_lt_i32 s8, 0
	s_movk_i32 s54, 0x161
	s_cselect_b32 s10, s54, 0x160
	s_mul_i32 s8, s10, s8
	s_add_i32 s8, s8, s9
	s_mul_hi_i32 s9, s8, 0x2e8ba2e9
	s_lshr_b32 s10, s9, 31
	s_ashr_i32 s9, s9, 3
	s_add_i32 s9, s9, s10
	s_lshl_b32 s10, s9, 1
	s_mul_i32 s9, s9, 44
	s_sub_i32 s8, s8, s9
	s_bfe_u32 s9, s8, 0x10007
	s_add_i32 s9, s8, s9
	s_bfe_i32 s11, s9, 0x80000
	s_and_b32 s9, s9, 0xfe
	s_sub_i32 s8, s8, s9
	s_sext_i32_i16 s11, s11
	s_sext_i32_i8 s8, s8
	v_lshrrev_b32_e32 v5, 2, v3
	v_lshlrev_b32_e32 v6, 1, v3
	v_and_b32_e32 v1, 0xc0, v1
	s_lshr_b32 s16, s11, 1
	s_add_i32 s44, s10, s8
	s_cmp_eq_u32 s42, 0x100
	s_cbranch_scc0 .Lwgm_p_0
	s_lshr_b32 s99, s2, 3
	s_and_b32 s44, s99, 15
	s_lshr_b32 s16, s99, 4
	s_and_b32 s98, s2, 7
	s_lshl_b32 s98, s98, 4
	s_add_i32 s44, s44, s98

.LBB0_72:
	s_add_i32 s59, s59, 1
	s_mul_i32 s4, s59, s62
	s_mul_hi_u32 s5, s59, s63
	s_add_i32 s5, s5, s4
	s_mul_i32 s4, s59, s63
	s_add_u32 s28, s4, s2
	s_addc_u32 s29, s5, s53
	v_cmp_gt_i64_e32 vcc, s[28:29], v[142:143]
	v_cmp_lt_i64_e64 s[4:5], s[28:29], v[140:141]
	s_cbranch_vccnz .LBB0_74
	s_cmp_eq_u32 s42, 0x100
	s_cbranch_scc0 .Lwgm_orig_0
	s_and_b32 s98, s2, 7
	s_lshr_b32 s99, s2, 3
	s_and_b32 s26, s99, 15
	s_lshr_b32 s101, s99, 4
	s_lshl_b32 s100, s59, 1
	s_add_i32 s22, s100, s101
	s_lshl_b32 s98, s98, 4
	s_add_i32 s26, s26, s98
	s_branch .LBB0_74

.LBB0_241:
	s_ashr_i32 s10, s12, 3
	s_add_i32 s10, s14, s10
	s_ashr_i32 s11, s10, 31
	s_lshr_b32 s11, s11, 27
	s_add_i32 s11, s10, s11
	s_ashr_i32 s12, s11, 5
	s_andn2_b32 s11, s11, 31
	s_sub_i32 s10, s10, s11
	s_bfe_u32 s11, s10, 0x10007
	s_add_i32 s11, s10, s11
	s_bfe_i32 s13, s11, 0x80000
	s_and_b32 s11, s11, 0xfe
	s_sub_i32 s10, s10, s11
	s_lshl_b32 s12, s12, 1
	s_sext_i32_i16 s13, s13
	s_sext_i32_i8 s10, s10
	s_add_i32 s14, s12, s10
	s_ashr_i32 s20, s13, 1
	s_cmp_eq_u32 s42, 0x100
	s_cbranch_scc0 .Lwgm_p_1
	s_lshr_b32 s99, s2, 3
	s_and_b32 s14, s99, 15
	s_lshr_b32 s20, s99, 4
	s_and_b32 s98, s2, 7
	s_lshl_b32 s98, s98, 4
	s_add_i32 s14, s14, s98

.LBB0_248:
	s_add_i32 s90, s90, 1
	s_mul_i32 s3, s90, s80
	s_mul_hi_u32 s12, s90, s81
	s_add_i32 s12, s12, s3
	s_mul_i32 s3, s90, s81
	s_add_u32 s62, s3, s2
	s_addc_u32 s63, s12, s82
	v_cmp_gt_i64_e32 vcc, s[62:63], v[174:175]
	v_cmp_lt_i64_e64 s[12:13], s[62:63], v[172:173]
	s_cbranch_vccnz .LBB0_254
	s_cmp_eq_u32 s42, 0x100
	s_cbranch_scc0 .Lwgm_orig_1
	s_and_b32 s98, s2, 7
	s_lshr_b32 s99, s2, 3
	s_and_b32 s60, s99, 15
	s_lshr_b32 s101, s99, 4
	s_lshl_b32 s100, s90, 1
	s_add_i32 s58, s100, s101
	s_lshl_b32 s98, s98, 4
	s_add_i32 s60, s60, s98
	s_branch .LBB0_254

.LBB0_517:
	s_or_b64 exec, exec, s[8:9]
	s_mov_b64 s[10:11], s[0:1]
	v_mov_b32_e32 v8, v157
	s_waitcnt lgkmcnt(0)
	v_cndmask_b32_e64 v0, 0, 1, s[24:25]
	s_barrier
	v_cmp_ne_u32_e64 s[8:9], 1, v0
	s_andn2_b64 vcc, exec, s[24:25]
	v_readfirstlane_b32 s24, v8
	s_cbranch_vccnz .LBB0_535
	v_lshlrev_b32_e32 v0, 4, v8
	v_add_u32_e32 v1, 0x2000, v0
	v_ashrrev_i32_e32 v2, 31, v1
	v_lshrrev_b32_e32 v2, 22, v2
	v_add_u32_e32 v2, v1, v2
	v_ashrrev_i32_e32 v9, 10, v2
	v_mul_i32_i24_e32 v2, 0x400, v9
	v_sub_u32_e32 v1, v1, v2
	v_lshrrev_b32_e32 v2, 4, v1
	v_bitop3_b32 v1, v2, v1, 32 bitop3:0x6c
	v_ashrrev_i32_e32 v2, 31, v1
	v_lshrrev_b32_e32 v2, 26, v2
	v_add_u32_e32 v2, v1, v2
	v_lshlrev_b32_e32 v3, 3, v9
	v_ashrrev_i32_e32 v10, 6, v2
	v_and_b32_e32 v3, -16, v3
	v_add_u32_e32 v3, v10, v3
	v_and_b32_e32 v4, 3, v10
	s_mov_b32 s12, 0x1fffe0
	v_lshrrev_b32_e32 v5, 2, v3
	v_lshlrev_b32_e32 v6, 1, v3
	v_and_b32_e32 v2, 0xc0, v2
	v_and_or_b32 v4, v3, s12, v4
	v_and_b32_e32 v5, 4, v5
	v_and_b32_e32 v6, 24, v6
	v_sub_u32_e32 v1, v1, v2
	v_mov_b32_e32 v2, 1
	v_or3_b32 v4, v4, v5, v6
	v_lshlrev_b32_e32 v5, 5, v9
	v_ashrrev_i16_sdwa v1, v2, sext(v1) dst_sel:DWORD dst_unused:UNUSED_PAD src0_sel:DWORD src1_sel:BYTE_0
	v_and_b32_e32 v5, 32, v5
	v_bfe_i32 v11, v1, 0, 16
	v_add_lshl_u32 v1, v5, v11, 1
	v_lshl_add_u32 v128, v4, 11, v1
	v_lshrrev_b32_e32 v250, 3, v157
	v_and_b32_e32 v251, 6, v250
	v_and_b32_e32 v252, 7, v157
	v_xor_b32_e32 v251, v251, v252
	v_lshlrev_b32_e32 v251, 4, v251
	v_and_b32_e32 v252, 12, v250
	v_lshlrev_b32_e32 v252, 1, v252
	v_and_b32_e32 v253, 16, v250
	v_lshrrev_b32_e32 v253, 2, v253
	v_or_b32_e32 v252, v252, v253
	v_and_b32_e32 v253, 35, v250
	v_or_b32_e32 v250, v252, v253
	v_mul_u32_u24_e32 v250, 0x800, v250
	v_add_u32_e32 v128, v250, v251
	v_add_u32_e32 v128, 0x20000, v128
	v_lshl_add_u32 v130, v3, 11, v1
	v_lshrrev_b32_e32 v250, 3, v157
	v_and_b32_e32 v251, 6, v250
	v_and_b32_e32 v252, 7, v157
	v_xor_b32_e32 v251, v251, v252
	v_lshlrev_b32_e32 v251, 4, v251
	v_mul_u32_u24_e32 v250, 0x800, v250
	v_add_u32_e32 v130, v250, v251
	v_add_u32_e32 v130, 0x20000, v130
	v_bfe_i32 v1, v8, 27, 1
	v_lshrrev_b32_e32 v1, 22, v1
	v_add_u32_e32 v1, v0, v1
	s_load_dwordx2 s[10:11], s[10:11], 0x80
	v_and_b32_e32 v1, 0xfffffc00, v1
	v_sub_u32_e32 v0, v0, v1
	v_lshrrev_b32_e32 v1, 4, v0
	v_ashrrev_i32_e32 v3, 31, v8
	v_bitop3_b32 v0, v1, v0, 32 bitop3:0x6c
	v_lshrrev_b32_e32 v3, 26, v3
	v_ashrrev_i32_e32 v1, 31, v0
	v_add_u32_e32 v3, v8, v3
	s_waitcnt lgkmcnt(0)
	s_add_u32 s3, s10, 0x6000000
	v_lshrrev_b32_e32 v1, 26, v1
	v_ashrrev_i32_e32 v13, 6, v3
	s_addc_u32 s35, s11, 0
	v_add_u32_e32 v1, v0, v1
	v_lshlrev_b32_e32 v3, 3, v13
	s_add_u32 s52, s10, 0xf00000
	v_ashrrev_i32_e32 v12, 6, v1
	v_and_b32_e32 v3, -16, v3
	s_addc_u32 s53, s11, 0
	v_add_u32_e32 v3, v12, v3
	v_and_b32_e32 v4, 3, v12
	s_ashr_i32 s55, s2, 31
	v_and_or_b32 v4, v3, s12, v4
	s_lshr_b32 s12, s55, 29
	s_add_i32 s12, s2, s12
	s_ashr_i32 s23, s24, 6
	s_ashr_i32 s13, s12, 3
	s_and_b32 s12, s12, -8
	s_ashr_i32 s25, s24, 8
	s_lshl_b32 s54, s23, 10
	s_sub_i32 s12, s2, s12
	s_cmp_lt_i32 s12, 0
	s_movk_i32 s56, 0x161
	s_cselect_b32 s14, s56, 0x160
	s_mul_i32 s12, s14, s12
	s_add_i32 s12, s12, s13
	s_mul_hi_i32 s13, s12, 0x2e8ba2e9
	s_lshr_b32 s14, s13, 31
	s_ashr_i32 s13, s13, 3
	s_add_i32 s13, s13, s14
	s_lshl_b32 s14, s13, 1
	s_mul_i32 s13, s13, 44
	s_sub_i32 s12, s12, s13
	s_bfe_u32 s13, s12, 0x10007
	s_add_i32 s13, s12, s13
	s_bfe_i32 s15, s13, 0x80000
	s_and_b32 s13, s13, 0xfe
	s_sub_i32 s12, s12, s13
	s_sext_i32_i16 s15, s15
	s_sext_i32_i8 s12, s12
	v_lshrrev_b32_e32 v5, 2, v3
	v_lshlrev_b32_e32 v6, 1, v3
	v_and_b32_e32 v1, 0xc0, v1
	s_lshr_b32 s22, s15, 1
	s_add_i32 s46, s14, s12
	s_cmp_eq_u32 s42, 0x100
	s_cbranch_scc0 .Lwgm_p_2
	s_lshr_b32 s99, s2, 3
	s_and_b32 s46, s99, 15
	s_lshr_b32 s22, s99, 4
	s_and_b32 s98, s2, 7
	s_lshl_b32 s98, s98, 4
	s_add_i32 s46, s46, s98

.LBB0_523:
	s_add_i32 s61, s61, 1
	s_mul_i32 s10, s61, s64
	s_mul_hi_u32 s11, s61, s65
	s_add_i32 s11, s11, s10
	s_mul_i32 s10, s61, s65
	s_add_u32 s30, s10, s2
	s_addc_u32 s31, s11, s55
	v_cmp_gt_i64_e32 vcc, s[30:31], v[142:143]
	v_cmp_lt_i64_e64 s[10:11], s[30:31], v[140:141]
	s_cbranch_vccnz .LBB0_525
	s_cmp_eq_u32 s42, 0x100
	s_cbranch_scc0 .Lwgm_orig_2
	s_and_b32 s98, s2, 7
	s_lshr_b32 s99, s2, 3
	s_and_b32 s28, s99, 15
	s_lshr_b32 s101, s99, 4
	s_lshl_b32 s100, s61, 1
	s_add_i32 s26, s100, s101
	s_lshl_b32 s98, s98, 4
	s_add_i32 s28, s28, s98
	s_branch .LBB0_525

.LBB0_687:
	s_or_b64 exec, exec, s[10:11]
	s_mov_b64 s[10:11], s[0:1]
	v_mov_b32_e32 v8, v157
	s_waitcnt lgkmcnt(0)
	s_barrier
	s_and_b64 vcc, exec, s[8:9]
	v_readfirstlane_b32 s24, v8
	s_cbranch_vccnz .LBB0_705
	v_lshlrev_b32_e32 v0, 4, v8
	v_add_u32_e32 v1, 0x2000, v0
	v_ashrrev_i32_e32 v2, 31, v1
	v_lshrrev_b32_e32 v2, 22, v2
	v_add_u32_e32 v2, v1, v2
	v_ashrrev_i32_e32 v9, 10, v2
	v_mul_i32_i24_e32 v2, 0x400, v9
	v_sub_u32_e32 v1, v1, v2
	v_lshrrev_b32_e32 v2, 4, v1
	v_bitop3_b32 v1, v2, v1, 32 bitop3:0x6c
	v_ashrrev_i32_e32 v2, 31, v1
	v_lshrrev_b32_e32 v2, 26, v2
	v_add_u32_e32 v2, v1, v2
	v_lshlrev_b32_e32 v3, 3, v9
	v_ashrrev_i32_e32 v10, 6, v2
	v_and_b32_e32 v3, -16, v3
	v_add_u32_e32 v3, v10, v3
	v_and_b32_e32 v4, 3, v10
	s_mov_b32 s12, 0x1fffe0
	v_lshrrev_b32_e32 v5, 2, v3
	v_lshlrev_b32_e32 v6, 1, v3
	v_and_b32_e32 v2, 0xc0, v2
	v_and_or_b32 v4, v3, s12, v4
	v_and_b32_e32 v5, 4, v5
	v_and_b32_e32 v6, 24, v6
	v_sub_u32_e32 v1, v1, v2
	v_mov_b32_e32 v2, 1
	v_or3_b32 v4, v4, v5, v6
	v_lshlrev_b32_e32 v5, 5, v9
	v_ashrrev_i16_sdwa v1, v2, sext(v1) dst_sel:DWORD dst_unused:UNUSED_PAD src0_sel:DWORD src1_sel:BYTE_0
	v_and_b32_e32 v5, 32, v5
	v_bfe_i32 v11, v1, 0, 16
	v_add_lshl_u32 v1, v5, v11, 1
	v_lshl_add_u32 v128, v4, 11, v1
	v_lshrrev_b32_e32 v250, 3, v157
	v_and_b32_e32 v251, 6, v250
	v_and_b32_e32 v252, 7, v157
	v_xor_b32_e32 v251, v251, v252
	v_lshlrev_b32_e32 v251, 4, v251
	v_and_b32_e32 v252, 12, v250
	v_lshlrev_b32_e32 v252, 1, v252
	v_and_b32_e32 v253, 16, v250
	v_lshrrev_b32_e32 v253, 2, v253
	v_or_b32_e32 v252, v252, v253
	v_and_b32_e32 v253, 35, v250
	v_or_b32_e32 v250, v252, v253
	v_mul_u32_u24_e32 v250, 0x800, v250
	v_add_u32_e32 v128, v250, v251
	v_add_u32_e32 v128, 0x20000, v128
	v_lshl_add_u32 v130, v3, 11, v1
	v_lshrrev_b32_e32 v250, 3, v157
	v_and_b32_e32 v251, 6, v250
	v_and_b32_e32 v252, 7, v157
	v_xor_b32_e32 v251, v251, v252
	v_lshlrev_b32_e32 v251, 4, v251
	v_mul_u32_u24_e32 v250, 0x800, v250
	v_add_u32_e32 v130, v250, v251
	v_add_u32_e32 v130, 0x20000, v130
	v_bfe_i32 v1, v8, 27, 1
	v_lshrrev_b32_e32 v1, 22, v1
	v_add_u32_e32 v1, v0, v1
	s_load_dwordx2 s[10:11], s[10:11], 0x80
	v_and_b32_e32 v1, 0xfffffc00, v1
	v_sub_u32_e32 v0, v0, v1
	v_lshrrev_b32_e32 v1, 4, v0
	v_ashrrev_i32_e32 v3, 31, v8
	v_bitop3_b32 v0, v1, v0, 32 bitop3:0x6c
	v_lshrrev_b32_e32 v3, 26, v3
	v_ashrrev_i32_e32 v1, 31, v0
	v_add_u32_e32 v3, v8, v3
	s_waitcnt lgkmcnt(0)
	s_add_u32 s3, s10, 0x6000000
	v_lshrrev_b32_e32 v1, 26, v1
	v_ashrrev_i32_e32 v13, 6, v3
	s_addc_u32 s35, s11, 0
	v_add_u32_e32 v1, v0, v1
	v_lshlrev_b32_e32 v3, 3, v13
	s_add_u32 s52, s10, 0x1a00000
	v_ashrrev_i32_e32 v12, 6, v1
	v_and_b32_e32 v3, -16, v3
	s_addc_u32 s53, s11, 0
	v_add_u32_e32 v3, v12, v3
	v_and_b32_e32 v4, 3, v12
	s_ashr_i32 s55, s2, 31
	v_and_or_b32 v4, v3, s12, v4
	s_lshr_b32 s12, s55, 29
	s_add_i32 s12, s2, s12
	s_ashr_i32 s23, s24, 6
	s_ashr_i32 s13, s12, 3
	s_and_b32 s12, s12, -8
	s_ashr_i32 s25, s24, 8
	s_lshl_b32 s54, s23, 10
	s_sub_i32 s12, s2, s12
	s_cmp_lt_i32 s12, 0
	s_movk_i32 s56, 0x161
	s_cselect_b32 s14, s56, 0x160
	s_mul_i32 s12, s14, s12
	s_add_i32 s12, s12, s13
	s_mul_hi_i32 s13, s12, 0x2e8ba2e9
	s_lshr_b32 s14, s13, 31
	s_ashr_i32 s13, s13, 3
	s_add_i32 s13, s13, s14
	s_lshl_b32 s14, s13, 1
	s_mul_i32 s13, s13, 44
	s_sub_i32 s12, s12, s13
	s_bfe_u32 s13, s12, 0x10007
	s_add_i32 s13, s12, s13
	s_bfe_i32 s15, s13, 0x80000
	s_and_b32 s13, s13, 0xfe
	s_sub_i32 s12, s12, s13
	s_sext_i32_i16 s15, s15
	s_sext_i32_i8 s12, s12
	v_lshrrev_b32_e32 v5, 2, v3
	v_lshlrev_b32_e32 v6, 1, v3
	v_and_b32_e32 v1, 0xc0, v1
	s_lshr_b32 s22, s15, 1
	s_add_i32 s46, s14, s12
	s_cmp_eq_u32 s42, 0x100
	s_cbranch_scc0 .Lwgm_p_3
	s_lshr_b32 s99, s2, 3
	s_and_b32 s46, s99, 15
	s_lshr_b32 s22, s99, 4
	s_and_b32 s98, s2, 7
	s_lshl_b32 s98, s98, 4
	s_add_i32 s46, s46, s98

.LBB0_1088:
	s_or_b64 exec, exec, s[6:7]
	s_mov_b64 s[6:7], s[0:1]
	v_mov_b32_e32 v8, v157
	s_waitcnt lgkmcnt(0)
	s_barrier
	s_and_b64 vcc, exec, s[8:9]
	v_readfirstlane_b32 s20, v8
	s_cbranch_vccnz .LBB0_1106
	v_lshlrev_b32_e32 v0, 4, v8
	v_add_u32_e32 v1, 0x2000, v0
	v_ashrrev_i32_e32 v2, 31, v1
	v_lshrrev_b32_e32 v2, 22, v2
	v_add_u32_e32 v2, v1, v2
	v_ashrrev_i32_e32 v9, 10, v2
	v_mul_i32_i24_e32 v2, 0x400, v9
	v_sub_u32_e32 v1, v1, v2
	v_lshrrev_b32_e32 v2, 4, v1
	v_bitop3_b32 v1, v2, v1, 32 bitop3:0x6c
	v_ashrrev_i32_e32 v2, 31, v1
	v_lshrrev_b32_e32 v2, 26, v2
	v_add_u32_e32 v2, v1, v2
	v_lshlrev_b32_e32 v3, 3, v9
	v_ashrrev_i32_e32 v10, 6, v2
	v_and_b32_e32 v3, -16, v3
	v_add_u32_e32 v3, v10, v3
	v_and_b32_e32 v4, 3, v10
	s_mov_b32 s8, 0x1fffe0
	v_lshrrev_b32_e32 v5, 2, v3
	v_lshlrev_b32_e32 v6, 1, v3
	v_and_b32_e32 v2, 0xc0, v2
	v_and_or_b32 v4, v3, s8, v4
	v_and_b32_e32 v5, 4, v5
	v_and_b32_e32 v6, 24, v6
	v_sub_u32_e32 v1, v1, v2
	v_mov_b32_e32 v2, 1
	v_or3_b32 v4, v4, v5, v6
	v_lshlrev_b32_e32 v5, 5, v9
	v_ashrrev_i16_sdwa v1, v2, sext(v1) dst_sel:DWORD dst_unused:UNUSED_PAD src0_sel:DWORD src1_sel:BYTE_0
	v_and_b32_e32 v5, 32, v5
	v_bfe_i32 v11, v1, 0, 16
	v_add_lshl_u32 v1, v5, v11, 1
	v_lshl_add_u32 v128, v4, 11, v1
	v_lshrrev_b32_e32 v250, 3, v157
	v_and_b32_e32 v251, 6, v250
	v_and_b32_e32 v252, 7, v157
	v_xor_b32_e32 v251, v251, v252
	v_lshlrev_b32_e32 v251, 4, v251
	v_and_b32_e32 v252, 12, v250
	v_lshlrev_b32_e32 v252, 1, v252
	v_and_b32_e32 v253, 16, v250
	v_lshrrev_b32_e32 v253, 2, v253
	v_or_b32_e32 v252, v252, v253
	v_and_b32_e32 v253, 35, v250
	v_or_b32_e32 v250, v252, v253
	v_mul_u32_u24_e32 v250, 0x800, v250
	v_add_u32_e32 v128, v250, v251
	v_add_u32_e32 v128, 0x20000, v128
	v_lshl_add_u32 v130, v3, 11, v1
	v_lshrrev_b32_e32 v250, 3, v157
	v_and_b32_e32 v251, 6, v250
	v_and_b32_e32 v252, 7, v157
	v_xor_b32_e32 v251, v251, v252
	v_lshlrev_b32_e32 v251, 4, v251
	v_mul_u32_u24_e32 v250, 0x800, v250
	v_add_u32_e32 v130, v250, v251
	v_add_u32_e32 v130, 0x20000, v130
	v_bfe_i32 v1, v8, 27, 1
	v_lshrrev_b32_e32 v1, 22, v1
	v_add_u32_e32 v1, v0, v1
	s_load_dwordx2 s[6:7], s[6:7], 0x80
	v_and_b32_e32 v1, 0xfffffc00, v1
	v_sub_u32_e32 v0, v0, v1
	v_lshrrev_b32_e32 v1, 4, v0
	v_ashrrev_i32_e32 v3, 31, v8
	v_bitop3_b32 v0, v1, v0, 32 bitop3:0x6c
	v_lshrrev_b32_e32 v3, 26, v3
	v_ashrrev_i32_e32 v1, 31, v0
	v_add_u32_e32 v3, v8, v3
	s_waitcnt lgkmcnt(0)
	s_add_u32 s3, s6, 0x6000000
	v_lshrrev_b32_e32 v1, 26, v1
	v_ashrrev_i32_e32 v13, 6, v3
	s_addc_u32 s33, s7, 0
	v_add_u32_e32 v1, v0, v1
	v_lshlrev_b32_e32 v3, 3, v13
	s_add_u32 s35, s6, 0x2500000
	v_ashrrev_i32_e32 v12, 6, v1
	v_and_b32_e32 v3, -16, v3
	s_addc_u32 s48, s7, 0
	v_add_u32_e32 v3, v12, v3
	v_and_b32_e32 v4, 3, v12
	s_ashr_i32 s50, s2, 31
	v_and_or_b32 v4, v3, s8, v4
	s_lshr_b32 s8, s50, 29
	s_add_i32 s8, s2, s8
	s_ashr_i32 s17, s20, 6
	s_ashr_i32 s9, s8, 3
	s_and_b32 s8, s8, -8
	s_ashr_i32 s21, s20, 8
	s_lshl_b32 s49, s17, 10
	s_sub_i32 s8, s2, s8
	s_cmp_lt_i32 s8, 0
	s_movk_i32 s51, 0x161
	s_cselect_b32 s10, s51, 0x160
	s_mul_i32 s8, s10, s8
	s_add_i32 s8, s8, s9
	s_mul_hi_i32 s9, s8, 0x2e8ba2e9
	s_lshr_b32 s10, s9, 31
	s_ashr_i32 s9, s9, 3
	s_add_i32 s9, s9, s10
	s_lshl_b32 s10, s9, 1
	s_mul_i32 s9, s9, 44
	s_sub_i32 s8, s8, s9
	s_bfe_u32 s9, s8, 0x10007
	s_add_i32 s9, s8, s9
	s_bfe_i32 s11, s9, 0x80000
	s_and_b32 s9, s9, 0xfe
	s_sub_i32 s8, s8, s9
	s_sext_i32_i16 s11, s11
	s_sext_i32_i8 s8, s8
	v_lshrrev_b32_e32 v5, 2, v3
	v_lshlrev_b32_e32 v6, 1, v3
	v_and_b32_e32 v1, 0xc0, v1
	s_lshr_b32 s16, s11, 1
	s_add_i32 s30, s10, s8
	s_cmp_eq_u32 s42, 0x100
	s_cbranch_scc0 .Lwgm_p_4
	s_lshr_b32 s99, s2, 3
	s_and_b32 s30, s99, 15
	s_lshr_b32 s16, s99, 4
	s_and_b32 s98, s2, 7
	s_lshl_b32 s98, s98, 4
	s_add_i32 s30, s30, s98

.LBB0_1094:
	s_add_i32 s56, s56, 1
	s_mul_i32 s6, s56, s59
	s_mul_hi_u32 s7, s56, s60
	s_add_i32 s7, s7, s6
	s_mul_i32 s6, s56, s60
	s_add_u32 s26, s6, s2
	s_addc_u32 s27, s7, s50
	v_cmp_gt_i64_e32 vcc, s[26:27], v[142:143]
	v_cmp_lt_i64_e64 s[6:7], s[26:27], v[140:141]
	s_cbranch_vccnz .LBB0_1096
	s_cmp_eq_u32 s42, 0x100
	s_cbranch_scc0 .Lwgm_orig_4
	s_and_b32 s98, s2, 7
	s_lshr_b32 s99, s2, 3
	s_and_b32 s24, s99, 15
	s_lshr_b32 s101, s99, 4
	s_lshl_b32 s100, s56, 1
	s_add_i32 s22, s100, s101
	s_lshl_b32 s98, s98, 4
	s_add_i32 s24, s24, s98
	s_branch .LBB0_1096
